# gated-merge phase: accumulator-rescale hooks and merge epilogue use counted vmcnt at first consumers instead of vmcnt(0) drains after each prefetch
# speedup vs baseline: 1.0212x; 1.0018x over previous
; __device__ __forceinline__ float bflo(unsigned u) { return __uint_as_float(u << 16); }
; __device__ __forceinline__ float bfhi(unsigned u) { return __uint_as_float(u & 0xffff0000u); }
;     __device__ __forceinline__ void hook(Acc& acc, const Unit& u, int stage, int wr, int wc, int fr, int fq) const {
;         const int row0 = u.pm * BM + wr * 64 + fr, col0 = u.pn * BM + wc * 32 + 8 * fq;
;         const bf16_t* ga = GT + stage * 1024 + col0;
;         u32x4 na[2], nb[2];
;         na[0] = *(const u32x4*)(ga + (size_t)row0 * GT_LD); nb[0] = *(const u32x4*)(ga + (size_t)row0 * GT_LD + 1024);
; #pragma unroll
;         for (int it = 0; it < 16; ++it) { const int bj = it >> 3, ai = (it >> 2) & 1, m = it & 3;
;             if (it + 1 < 16) { const int bj2 = (it + 1) >> 3, ai2 = ((it + 1) >> 2) & 1, m2 = (it + 1) & 3; const bf16_t* p = ga + (size_t)(row0 + ai2 * HALF + m2 * 16) * GT_LD + bj2 * HALF;
;                 na[(it + 1) & 1] = *(const u32x4*)p; nb[(it + 1) & 1] = *(const u32x4*)(p + 1024); }
;             const u32x4 a = na[it & 1], b = nb[it & 1];
;             f32x4 v0 = acc[ai][bj][m][0], v1 = acc[ai][bj][m][1];
;             v0[0] *= bflo(a.x) * __builtin_amdgcn_rcpf(bflo(b.x)); v0[1] *= bfhi(a.x) * __builtin_amdgcn_rcpf(bfhi(b.x)); v0[2] *= bflo(a.y) * __builtin_amdgcn_rcpf(bflo(b.y)); v0[3] *= bfhi(a.y) * __builtin_amdgcn_rcpf(bfhi(b.y));
;             v1[0] *= bflo(a.z) * __builtin_amdgcn_rcpf(bflo(b.z)); v1[1] *= bfhi(a.z) * __builtin_amdgcn_rcpf(bfhi(b.z)); v1[2] *= bflo(a.w) * __builtin_amdgcn_rcpf(bflo(b.w)); v1[3] *= bfhi(a.w) * __builtin_amdgcn_rcpf(bfhi(b.w));
;             acc[ai][bj][m][0] = v0; acc[ai][bj][m][1] = v1;
;             asm volatile("" ::: "memory"); }
;     }
; template <class Epi, class Sched>
; __device__ __forceinline__ void gemm_phase(LAS unsigned char* lds, const Gemm g, const Sched& S, const Epi& E) {
;     ...
;             if constexpr (Epi::HOOKS) { if (cur.kind == 3 && (t == 4 || t == 12)) { int fr_ = fr, fq_ = fq; asm volatile("" : "+v"(fr_), "+v"(fq_)); E.hook(acc, cur, t == 4 ? 0 : 1, wr, wc, fr_, fq_); } }
.LBB0_289:
	s_andn2_b64 vcc, exec, s[0:1]
	s_cbranch_vccnz .LBB0_291
	s_cmp_eq_u32 s19, 4
	v_mov_b32_e32 v130, v181
	v_mov_b32_e32 v131, v185
	s_cselect_b32 s0, 0, 0x800
	v_add_u32_e32 v180, s67, v130
	v_lshl_add_u32 v130, v131, 3, s85
	s_add_u32 s0, s56, s0
	s_addc_u32 s1, s57, 0
	v_ashrrev_i32_e32 v131, 31, v130
	v_lshl_add_u64 v[172:173], v[130:131], 1, s[0:1]
	v_add_u32_e32 v130, 16, v180
	v_mad_i64_i32 v[176:177], s[0:1], v130, s33, v[172:173]
	v_mad_i64_i32 v[178:179], s[0:1], v180, s33, v[172:173]
	global_load_dwordx4 v[130:133], v[176:177], off
	global_load_dwordx4 v[134:137], v[176:177], off offset:2048
	global_load_dwordx4 v[138:141], v[178:179], off offset:2048
	global_load_dwordx4 v[142:145], v[178:179], off
	s_waitcnt lgkmcnt(0)
	s_waitcnt vmcnt(1)
	v_lshlrev_b32_e32 v146, 16, v138
	v_and_b32_e32 v138, 0xffff0000, v138
	v_rcp_f32_e32 v147, v138
	v_lshlrev_b32_e32 v138, 16, v139
	v_and_b32_e32 v139, 0xffff0000, v139
	v_rcp_f32_e32 v138, v138
	v_rcp_f32_e32 v139, v139
	s_waitcnt vmcnt(0)
	v_lshlrev_b32_e32 v148, 16, v142
	v_and_b32_e32 v149, 0xffff0000, v142
	v_lshlrev_b32_e32 v142, 16, v143
	v_and_b32_e32 v143, 0xffff0000, v143
	v_pk_mul_f32 v[138:139], v[138:139], v[142:143]
	v_lshlrev_b32_e32 v142, 16, v144
	v_pk_mul_f32 v[128:129], v[128:129], v[138:139]
	v_lshlrev_b32_e32 v138, 16, v140
	v_and_b32_e32 v139, 0xffff0000, v140
	v_rcp_f32_e32 v138, v138
	v_rcp_f32_e32 v139, v139
	v_and_b32_e32 v143, 0xffff0000, v144
	v_lshlrev_b32_e32 v140, 16, v145
	v_rcp_f32_e32 v146, v146
	v_pk_mul_f32 v[138:139], v[138:139], v[142:143]
	v_pk_mul_f32 v[146:147], v[146:147], v[148:149]
	v_pk_mul_f32 v[122:123], v[122:123], v[138:139]
	v_lshlrev_b32_e32 v138, 16, v141
	v_and_b32_e32 v139, 0xffff0000, v141
	v_rcp_f32_e32 v138, v138
	v_rcp_f32_e32 v139, v139
	v_and_b32_e32 v141, 0xffff0000, v145
	v_pk_mul_f32 v[126:127], v[126:127], v[146:147]
	v_lshlrev_b32_e32 v146, 16, v134
	v_pk_mul_f32 v[138:139], v[138:139], v[140:141]
	v_and_b32_e32 v134, 0xffff0000, v134
	v_pk_mul_f32 v[124:125], v[124:125], v[138:139]
	v_add_u32_e32 v138, 32, v180
	v_mad_i64_i32 v[166:167], s[0:1], v138, s33, v[172:173]
	global_load_dwordx4 v[138:141], v[166:167], off
	global_load_dwordx4 v[142:145], v[166:167], off offset:2048
	v_lshlrev_b32_e32 v148, 16, v130
	v_and_b32_e32 v149, 0xffff0000, v130
	v_lshlrev_b32_e32 v130, 16, v135
	v_rcp_f32_e32 v147, v134
	v_rcp_f32_e32 v134, v130
	v_and_b32_e32 v130, 0xffff0000, v135
	v_rcp_f32_e32 v135, v130
	v_lshlrev_b32_e32 v130, 16, v131
	v_and_b32_e32 v131, 0xffff0000, v131
	v_pk_mul_f32 v[130:131], v[134:135], v[130:131]
	v_lshlrev_b32_e32 v134, 16, v132
	v_pk_mul_f32 v[120:121], v[120:121], v[130:131]
	v_lshlrev_b32_e32 v130, 16, v136
	v_and_b32_e32 v131, 0xffff0000, v136
	v_rcp_f32_e32 v130, v130
	v_rcp_f32_e32 v131, v131
	v_and_b32_e32 v135, 0xffff0000, v132
	v_lshlrev_b32_e32 v132, 16, v133
	v_and_b32_e32 v133, 0xffff0000, v133
	v_pk_mul_f32 v[130:131], v[130:131], v[134:135]
	v_rcp_f32_e32 v146, v146
	v_pk_mul_f32 v[114:115], v[114:115], v[130:131]
	v_lshlrev_b32_e32 v130, 16, v137
	v_and_b32_e32 v131, 0xffff0000, v137
	v_rcp_f32_e32 v130, v130
	v_rcp_f32_e32 v131, v131
	v_pk_mul_f32 v[146:147], v[146:147], v[148:149]
	v_pk_mul_f32 v[130:131], v[130:131], v[132:133]
	s_nop 0
	v_pk_mul_f32 v[116:117], v[116:117], v[130:131]
	v_add_u32_e32 v130, 48, v180
	v_mad_i64_i32 v[164:165], s[0:1], v130, s33, v[172:173]
	global_load_dwordx4 v[130:133], v[164:165], off
	global_load_dwordx4 v[134:137], v[164:165], off offset:2048
	v_pk_mul_f32 v[118:119], v[118:119], v[146:147]
	s_waitcnt lgkmcnt(0)
	s_waitcnt vmcnt(3)
	v_lshlrev_b32_e32 v148, 16, v138
	s_waitcnt vmcnt(2)
	v_lshlrev_b32_e32 v146, 16, v142
	v_and_b32_e32 v142, 0xffff0000, v142
	v_and_b32_e32 v149, 0xffff0000, v138
	v_lshlrev_b32_e32 v138, 16, v143
	v_rcp_f32_e32 v147, v142
	v_rcp_f32_e32 v142, v138
	v_and_b32_e32 v138, 0xffff0000, v143
	v_rcp_f32_e32 v143, v138
	v_lshlrev_b32_e32 v138, 16, v139
	v_and_b32_e32 v139, 0xffff0000, v139
	v_rcp_f32_e32 v146, v146
	v_pk_mul_f32 v[138:139], v[142:143], v[138:139]
	v_lshlrev_b32_e32 v142, 16, v140
	v_pk_mul_f32 v[112:113], v[112:113], v[138:139]
	v_lshlrev_b32_e32 v138, 16, v144
	v_and_b32_e32 v139, 0xffff0000, v144
	v_rcp_f32_e32 v138, v138
	v_rcp_f32_e32 v139, v139
	v_and_b32_e32 v143, 0xffff0000, v140
	v_lshlrev_b32_e32 v140, 16, v141
	v_and_b32_e32 v141, 0xffff0000, v141
	v_pk_mul_f32 v[138:139], v[138:139], v[142:143]
	v_pk_mul_f32 v[146:147], v[146:147], v[148:149]
	v_pk_mul_f32 v[106:107], v[106:107], v[138:139]
	v_lshlrev_b32_e32 v138, 16, v145
	v_and_b32_e32 v139, 0xffff0000, v145
	v_rcp_f32_e32 v138, v138
	v_rcp_f32_e32 v139, v139
	v_pk_mul_f32 v[110:111], v[110:111], v[146:147]
	v_pk_mul_f32 v[138:139], v[138:139], v[140:141]
	s_nop 0
	v_pk_mul_f32 v[108:109], v[108:109], v[138:139]
	v_add_u32_e32 v138, 0x80, v180
	v_mad_i64_i32 v[168:169], s[0:1], v138, s33, v[172:173]
	global_load_dwordx4 v[138:141], v[168:169], off
	global_load_dwordx4 v[142:145], v[168:169], off offset:2048
	s_waitcnt vmcnt(2)
; __device__ __forceinline__ float bflo(unsigned u) { return __uint_as_float(u << 16); }
; __device__ __forceinline__ float bfhi(unsigned u) { return __uint_as_float(u & 0xffff0000u); }
;     __device__ __forceinline__ void hook(Acc& acc, const Unit& u, int stage, int wr, int wc, int fr, int fq) const {
;     ...
;         for (int it = 0; it < 16; ++it) { const int bj = it >> 3, ai = (it >> 2) & 1, m = it & 3;
;             if (it + 1 < 16) { const int bj2 = (it + 1) >> 3, ai2 = ((it + 1) >> 2) & 1, m2 = (it + 1) & 3; const bf16_t* p = ga + (size_t)(row0 + ai2 * HALF + m2 * 16) * GT_LD + bj2 * HALF;
;                 na[(it + 1) & 1] = *(const u32x4*)p; nb[(it + 1) & 1] = *(const u32x4*)(p + 1024); }
;             const u32x4 a = na[it & 1], b = nb[it & 1];
;             f32x4 v0 = acc[ai][bj][m][0], v1 = acc[ai][bj][m][1];
;             v0[0] *= bflo(a.x) * __builtin_amdgcn_rcpf(bflo(b.x)); v0[1] *= bfhi(a.x) * __builtin_amdgcn_rcpf(bfhi(b.x)); v0[2] *= bflo(a.y) * __builtin_amdgcn_rcpf(bflo(b.y)); v0[3] *= bfhi(a.y) * __builtin_amdgcn_rcpf(bfhi(b.y));
;             v1[0] *= bflo(a.z) * __builtin_amdgcn_rcpf(bflo(b.z)); v1[1] *= bfhi(a.z) * __builtin_amdgcn_rcpf(bfhi(b.z)); v1[2] *= bflo(a.w) * __builtin_amdgcn_rcpf(bflo(b.w)); v1[3] *= bfhi(a.w) * __builtin_amdgcn_rcpf(bfhi(b.w));
;             acc[ai][bj][m][0] = v0; acc[ai][bj][m][1] = v1;
;             asm volatile("" ::: "memory"); }
	v_lshlrev_b32_e32 v146, 16, v134
	v_and_b32_e32 v134, 0xffff0000, v134
	v_lshlrev_b32_e32 v148, 16, v130
	v_and_b32_e32 v149, 0xffff0000, v130
	v_lshlrev_b32_e32 v130, 16, v135
	v_rcp_f32_e32 v147, v134
	v_rcp_f32_e32 v134, v130
	v_and_b32_e32 v130, 0xffff0000, v135
	v_rcp_f32_e32 v135, v130
	v_lshlrev_b32_e32 v130, 16, v131
	v_and_b32_e32 v131, 0xffff0000, v131
	v_rcp_f32_e32 v146, v146
	v_pk_mul_f32 v[130:131], v[134:135], v[130:131]
	v_lshlrev_b32_e32 v134, 16, v132
	v_pk_mul_f32 v[104:105], v[104:105], v[130:131]
	v_lshlrev_b32_e32 v130, 16, v136
	v_and_b32_e32 v131, 0xffff0000, v136
	v_rcp_f32_e32 v130, v130
	v_rcp_f32_e32 v131, v131
	v_and_b32_e32 v135, 0xffff0000, v132
	v_lshlrev_b32_e32 v132, 16, v133
	v_and_b32_e32 v133, 0xffff0000, v133
	v_pk_mul_f32 v[130:131], v[130:131], v[134:135]
	v_pk_mul_f32 v[146:147], v[146:147], v[148:149]
	v_pk_mul_f32 v[98:99], v[98:99], v[130:131]
	v_lshlrev_b32_e32 v130, 16, v137
	v_and_b32_e32 v131, 0xffff0000, v137
	v_rcp_f32_e32 v130, v130
	v_rcp_f32_e32 v131, v131
	v_pk_mul_f32 v[102:103], v[102:103], v[146:147]
	v_pk_mul_f32 v[130:131], v[130:131], v[132:133]
	s_nop 0
	v_pk_mul_f32 v[100:101], v[100:101], v[130:131]
	v_add_u32_e32 v130, 0x90, v180
	v_mad_i64_i32 v[170:171], s[0:1], v130, s33, v[172:173]
	global_load_dwordx4 v[130:133], v[170:171], off
	global_load_dwordx4 v[146:149], v[170:171], off offset:2048
	s_waitcnt lgkmcnt(0)
	s_waitcnt vmcnt(3)
	v_lshlrev_b32_e32 v136, 16, v138
	s_waitcnt vmcnt(2)
	v_lshlrev_b32_e32 v134, 16, v142
	v_and_b32_e32 v135, 0xffff0000, v142
	v_rcp_f32_e32 v134, v134
	v_rcp_f32_e32 v135, v135
	v_and_b32_e32 v137, 0xffff0000, v138
	v_pk_mul_f32 v[134:135], v[134:135], v[136:137]
	s_nop 0
	v_pk_mul_f32 v[94:95], v[94:95], v[134:135]
	v_lshlrev_b32_e32 v134, 16, v143
	v_and_b32_e32 v135, 0xffff0000, v143
	v_rcp_f32_e32 v134, v134
	v_rcp_f32_e32 v135, v135
	v_lshlrev_b32_e32 v136, 16, v139
	v_and_b32_e32 v137, 0xffff0000, v139
	v_pk_mul_f32 v[134:135], v[134:135], v[136:137]
	s_nop 0
	v_pk_mul_f32 v[96:97], v[96:97], v[134:135]
	v_lshlrev_b32_e32 v134, 16, v144
	v_and_b32_e32 v135, 0xffff0000, v144
	v_rcp_f32_e32 v134, v134
	v_rcp_f32_e32 v135, v135
	v_lshlrev_b32_e32 v136, 16, v140
	v_and_b32_e32 v137, 0xffff0000, v140
	v_pk_mul_f32 v[134:135], v[134:135], v[136:137]
	s_nop 0
	v_pk_mul_f32 v[90:91], v[90:91], v[134:135]
	v_lshlrev_b32_e32 v134, 16, v145
	v_and_b32_e32 v135, 0xffff0000, v145
	v_rcp_f32_e32 v134, v134
	v_rcp_f32_e32 v135, v135
	v_lshlrev_b32_e32 v136, 16, v141
	v_and_b32_e32 v137, 0xffff0000, v141
	v_pk_mul_f32 v[134:135], v[134:135], v[136:137]
	s_nop 0
	v_pk_mul_f32 v[92:93], v[92:93], v[134:135]
	v_add_u32_e32 v134, 0xa0, v180
	v_mad_i64_i32 v[174:175], s[0:1], v134, s33, v[172:173]
	s_waitcnt vmcnt(0)
	v_lshlrev_b32_e32 v138, 16, v146
	v_and_b32_e32 v139, 0xffff0000, v146
	global_load_dwordx4 v[134:137], v[174:175], off
	global_load_dwordx4 v[142:145], v[174:175], off offset:2048
	v_rcp_f32_e32 v138, v138
	v_rcp_f32_e32 v139, v139
	v_lshlrev_b32_e32 v140, 16, v130
	v_and_b32_e32 v141, 0xffff0000, v130
	v_lshlrev_b32_e32 v130, 16, v147
	v_pk_mul_f32 v[138:139], v[138:139], v[140:141]
	s_waitcnt lgkmcnt(0)
	s_waitcnt vmcnt(0)
	v_lshlrev_b32_e32 v146, 16, v142
	v_pk_mul_f32 v[86:87], v[86:87], v[138:139]
	v_rcp_f32_e32 v138, v130
	v_and_b32_e32 v130, 0xffff0000, v147
	v_rcp_f32_e32 v139, v130
	v_lshlrev_b32_e32 v130, 16, v131
	v_and_b32_e32 v131, 0xffff0000, v131
	v_and_b32_e32 v142, 0xffff0000, v142
	v_pk_mul_f32 v[130:131], v[138:139], v[130:131]
	v_lshlrev_b32_e32 v138, 16, v132
	v_pk_mul_f32 v[88:89], v[88:89], v[130:131]
	v_lshlrev_b32_e32 v130, 16, v148
	v_and_b32_e32 v131, 0xffff0000, v148
	v_rcp_f32_e32 v130, v130
	v_rcp_f32_e32 v131, v131
	v_and_b32_e32 v139, 0xffff0000, v132
	v_lshlrev_b32_e32 v132, 16, v133
	v_and_b32_e32 v133, 0xffff0000, v133
	v_pk_mul_f32 v[130:131], v[130:131], v[138:139]
	v_lshlrev_b32_e32 v148, 16, v134
	v_pk_mul_f32 v[82:83], v[82:83], v[130:131]
	v_lshlrev_b32_e32 v130, 16, v149
	v_and_b32_e32 v131, 0xffff0000, v149
	v_rcp_f32_e32 v130, v130
	v_rcp_f32_e32 v131, v131
	v_and_b32_e32 v149, 0xffff0000, v134
	v_lshlrev_b32_e32 v134, 16, v143
	v_rcp_f32_e32 v147, v142
	v_pk_mul_f32 v[130:131], v[130:131], v[132:133]
	v_rcp_f32_e32 v142, v134
	v_pk_mul_f32 v[84:85], v[84:85], v[130:131]
	v_add_u32_e32 v130, 0xb0, v180
	v_mad_i64_i32 v[172:173], s[0:1], v130, s33, v[172:173]
	global_load_dwordx4 v[130:133], v[172:173], off
	global_load_dwordx4 v[138:141], v[172:173], off offset:2048
	v_and_b32_e32 v134, 0xffff0000, v143
	v_rcp_f32_e32 v143, v134
	v_lshlrev_b32_e32 v134, 16, v135
	v_and_b32_e32 v135, 0xffff0000, v135
	v_pk_mul_f32 v[134:135], v[142:143], v[134:135]
	v_lshlrev_b32_e32 v142, 16, v136
	v_pk_mul_f32 v[80:81], v[80:81], v[134:135]
	v_lshlrev_b32_e32 v134, 16, v144
	v_and_b32_e32 v135, 0xffff0000, v144
	v_rcp_f32_e32 v134, v134
	v_rcp_f32_e32 v135, v135
	v_and_b32_e32 v143, 0xffff0000, v136
	v_lshlrev_b32_e32 v136, 16, v137
	v_and_b32_e32 v137, 0xffff0000, v137
	v_pk_mul_f32 v[134:135], v[134:135], v[142:143]
	v_rcp_f32_e32 v146, v146
	v_pk_mul_f32 v[74:75], v[74:75], v[134:135]
	v_lshlrev_b32_e32 v134, 16, v145
	v_and_b32_e32 v135, 0xffff0000, v145
	v_rcp_f32_e32 v134, v134
	v_rcp_f32_e32 v135, v135
	v_pk_mul_f32 v[146:147], v[146:147], v[148:149]
	v_pk_mul_f32 v[134:135], v[134:135], v[136:137]
	s_nop 0
	v_pk_mul_f32 v[76:77], v[76:77], v[134:135]
	global_load_dwordx4 v[134:137], v[178:179], off offset:256
	global_load_dwordx4 v[142:145], v[178:179], off offset:2304
	v_pk_mul_f32 v[78:79], v[78:79], v[146:147]
	s_waitcnt lgkmcnt(0)
	s_waitcnt vmcnt(3)
	v_lshlrev_b32_e32 v148, 16, v130
	s_waitcnt vmcnt(2)
; __device__ __forceinline__ float bflo(unsigned u) { return __uint_as_float(u << 16); }
; __device__ __forceinline__ float bfhi(unsigned u) { return __uint_as_float(u & 0xffff0000u); }
;     __device__ __forceinline__ void hook(Acc& acc, const Unit& u, int stage, int wr, int wc, int fr, int fq) const {
;     ...
;         for (int it = 0; it < 16; ++it) { const int bj = it >> 3, ai = (it >> 2) & 1, m = it & 3;
;             if (it + 1 < 16) { const int bj2 = (it + 1) >> 3, ai2 = ((it + 1) >> 2) & 1, m2 = (it + 1) & 3; const bf16_t* p = ga + (size_t)(row0 + ai2 * HALF + m2 * 16) * GT_LD + bj2 * HALF;
;                 na[(it + 1) & 1] = *(const u32x4*)p; nb[(it + 1) & 1] = *(const u32x4*)(p + 1024); }
;             const u32x4 a = na[it & 1], b = nb[it & 1];
;             f32x4 v0 = acc[ai][bj][m][0], v1 = acc[ai][bj][m][1];
;             v0[0] *= bflo(a.x) * __builtin_amdgcn_rcpf(bflo(b.x)); v0[1] *= bfhi(a.x) * __builtin_amdgcn_rcpf(bfhi(b.x)); v0[2] *= bflo(a.y) * __builtin_amdgcn_rcpf(bflo(b.y)); v0[3] *= bfhi(a.y) * __builtin_amdgcn_rcpf(bfhi(b.y));
;             v1[0] *= bflo(a.z) * __builtin_amdgcn_rcpf(bflo(b.z)); v1[1] *= bfhi(a.z) * __builtin_amdgcn_rcpf(bfhi(b.z)); v1[2] *= bflo(a.w) * __builtin_amdgcn_rcpf(bflo(b.w)); v1[3] *= bfhi(a.w) * __builtin_amdgcn_rcpf(bfhi(b.w));
;             acc[ai][bj][m][0] = v0; acc[ai][bj][m][1] = v1;
;             asm volatile("" ::: "memory"); }
	v_lshlrev_b32_e32 v146, 16, v138
	v_and_b32_e32 v138, 0xffff0000, v138
	v_and_b32_e32 v149, 0xffff0000, v130
	v_lshlrev_b32_e32 v130, 16, v139
	v_rcp_f32_e32 v147, v138
	v_rcp_f32_e32 v138, v130
	v_and_b32_e32 v130, 0xffff0000, v139
	v_rcp_f32_e32 v139, v130
	v_lshlrev_b32_e32 v130, 16, v131
	v_and_b32_e32 v131, 0xffff0000, v131
	v_rcp_f32_e32 v146, v146
	v_pk_mul_f32 v[130:131], v[138:139], v[130:131]
	v_lshlrev_b32_e32 v138, 16, v132
	v_pk_mul_f32 v[72:73], v[72:73], v[130:131]
	v_lshlrev_b32_e32 v130, 16, v140
	v_and_b32_e32 v131, 0xffff0000, v140
	v_rcp_f32_e32 v130, v130
	v_rcp_f32_e32 v131, v131
	v_and_b32_e32 v139, 0xffff0000, v132
	v_lshlrev_b32_e32 v132, 16, v133
	v_and_b32_e32 v133, 0xffff0000, v133
	v_pk_mul_f32 v[130:131], v[130:131], v[138:139]
	v_pk_mul_f32 v[146:147], v[146:147], v[148:149]
	v_pk_mul_f32 v[66:67], v[66:67], v[130:131]
	v_lshlrev_b32_e32 v130, 16, v141
	v_and_b32_e32 v131, 0xffff0000, v141
	v_rcp_f32_e32 v130, v130
	v_rcp_f32_e32 v131, v131
	v_pk_mul_f32 v[70:71], v[70:71], v[146:147]
	s_waitcnt vmcnt(0)
	v_lshlrev_b32_e32 v146, 16, v142
	v_and_b32_e32 v142, 0xffff0000, v142
	v_pk_mul_f32 v[130:131], v[130:131], v[132:133]
	v_lshlrev_b32_e32 v148, 16, v134
	v_pk_mul_f32 v[68:69], v[68:69], v[130:131]
	global_load_dwordx4 v[130:133], v[176:177], off offset:256
	global_load_dwordx4 v[138:141], v[176:177], off offset:2304
	v_and_b32_e32 v149, 0xffff0000, v134
	v_lshlrev_b32_e32 v134, 16, v143
	v_rcp_f32_e32 v147, v142
	v_rcp_f32_e32 v142, v134
	v_and_b32_e32 v134, 0xffff0000, v143
	v_rcp_f32_e32 v143, v134
	v_lshlrev_b32_e32 v134, 16, v135
	v_and_b32_e32 v135, 0xffff0000, v135
	v_pk_mul_f32 v[134:135], v[142:143], v[134:135]
	v_lshlrev_b32_e32 v142, 16, v136
	v_pk_mul_f32 v[64:65], v[64:65], v[134:135]
	v_lshlrev_b32_e32 v134, 16, v144
	v_and_b32_e32 v135, 0xffff0000, v144
	v_rcp_f32_e32 v134, v134
	v_rcp_f32_e32 v135, v135
	v_and_b32_e32 v143, 0xffff0000, v136
	v_lshlrev_b32_e32 v136, 16, v137
	v_and_b32_e32 v137, 0xffff0000, v137
	v_pk_mul_f32 v[134:135], v[134:135], v[142:143]
	v_rcp_f32_e32 v146, v146
	v_pk_mul_f32 v[58:59], v[58:59], v[134:135]
	v_lshlrev_b32_e32 v134, 16, v145
	v_and_b32_e32 v135, 0xffff0000, v145
	v_rcp_f32_e32 v134, v134
	v_rcp_f32_e32 v135, v135
	v_pk_mul_f32 v[146:147], v[146:147], v[148:149]
	v_pk_mul_f32 v[134:135], v[134:135], v[136:137]
	s_nop 0
	v_pk_mul_f32 v[60:61], v[60:61], v[134:135]
	global_load_dwordx4 v[134:137], v[166:167], off offset:256
	global_load_dwordx4 v[142:145], v[166:167], off offset:2304
	v_pk_mul_f32 v[62:63], v[62:63], v[146:147]
	s_waitcnt lgkmcnt(0)
	s_waitcnt vmcnt(3)
	v_lshlrev_b32_e32 v148, 16, v130
	s_waitcnt vmcnt(2)
	v_lshlrev_b32_e32 v146, 16, v138
	v_and_b32_e32 v138, 0xffff0000, v138
	v_and_b32_e32 v149, 0xffff0000, v130
	v_lshlrev_b32_e32 v130, 16, v139
	v_rcp_f32_e32 v147, v138
	v_rcp_f32_e32 v138, v130
	v_and_b32_e32 v130, 0xffff0000, v139
	v_rcp_f32_e32 v139, v130
	v_lshlrev_b32_e32 v130, 16, v131
	v_and_b32_e32 v131, 0xffff0000, v131
	v_rcp_f32_e32 v146, v146
	v_pk_mul_f32 v[130:131], v[138:139], v[130:131]
	v_lshlrev_b32_e32 v138, 16, v132
	v_pk_mul_f32 v[56:57], v[56:57], v[130:131]
	v_lshlrev_b32_e32 v130, 16, v140
	v_and_b32_e32 v131, 0xffff0000, v140
	v_rcp_f32_e32 v130, v130
	v_rcp_f32_e32 v131, v131
	v_and_b32_e32 v139, 0xffff0000, v132
	v_lshlrev_b32_e32 v132, 16, v133
	v_and_b32_e32 v133, 0xffff0000, v133
	v_pk_mul_f32 v[130:131], v[130:131], v[138:139]
	v_pk_mul_f32 v[146:147], v[146:147], v[148:149]
	v_pk_mul_f32 v[50:51], v[50:51], v[130:131]
	v_lshlrev_b32_e32 v130, 16, v141
	v_and_b32_e32 v131, 0xffff0000, v141
	v_rcp_f32_e32 v130, v130
	v_rcp_f32_e32 v131, v131
	v_pk_mul_f32 v[54:55], v[54:55], v[146:147]
	v_pk_mul_f32 v[130:131], v[130:131], v[132:133]
	s_nop 0
	v_pk_mul_f32 v[52:53], v[52:53], v[130:131]
	global_load_dwordx4 v[130:133], v[164:165], off offset:256
	global_load_dwordx4 v[138:141], v[164:165], off offset:2304
	s_waitcnt vmcnt(2)
	v_lshlrev_b32_e32 v146, 16, v142
	v_and_b32_e32 v142, 0xffff0000, v142
	v_lshlrev_b32_e32 v148, 16, v134
	v_and_b32_e32 v149, 0xffff0000, v134
	v_lshlrev_b32_e32 v134, 16, v143
	v_rcp_f32_e32 v147, v142
	v_rcp_f32_e32 v142, v134
	v_and_b32_e32 v134, 0xffff0000, v143
	v_rcp_f32_e32 v143, v134
	v_lshlrev_b32_e32 v134, 16, v135
	v_and_b32_e32 v135, 0xffff0000, v135
	v_pk_mul_f32 v[134:135], v[142:143], v[134:135]
	v_lshlrev_b32_e32 v142, 16, v136
	v_pk_mul_f32 v[48:49], v[48:49], v[134:135]
	v_lshlrev_b32_e32 v134, 16, v144
	v_and_b32_e32 v135, 0xffff0000, v144
	v_rcp_f32_e32 v134, v134
	v_rcp_f32_e32 v135, v135
	v_and_b32_e32 v143, 0xffff0000, v136
	v_lshlrev_b32_e32 v136, 16, v137
	v_and_b32_e32 v137, 0xffff0000, v137
	v_pk_mul_f32 v[134:135], v[134:135], v[142:143]
	v_rcp_f32_e32 v146, v146
	v_pk_mul_f32 v[42:43], v[42:43], v[134:135]
	v_lshlrev_b32_e32 v134, 16, v145
	v_and_b32_e32 v135, 0xffff0000, v145
	v_rcp_f32_e32 v134, v134
	v_rcp_f32_e32 v135, v135
	v_pk_mul_f32 v[146:147], v[146:147], v[148:149]
	v_pk_mul_f32 v[134:135], v[134:135], v[136:137]
	s_nop 0
	v_pk_mul_f32 v[44:45], v[44:45], v[134:135]
	global_load_dwordx4 v[134:137], v[168:169], off offset:256
	global_load_dwordx4 v[142:145], v[168:169], off offset:2304
	v_pk_mul_f32 v[46:47], v[46:47], v[146:147]
	s_waitcnt lgkmcnt(0)
	s_waitcnt vmcnt(3)
	v_lshlrev_b32_e32 v148, 16, v130
	s_waitcnt vmcnt(2)
; __device__ __forceinline__ float bflo(unsigned u) { return __uint_as_float(u << 16); }
; __device__ __forceinline__ float bfhi(unsigned u) { return __uint_as_float(u & 0xffff0000u); }
;     __device__ __forceinline__ void hook(Acc& acc, const Unit& u, int stage, int wr, int wc, int fr, int fq) const {
;     ...
;         for (int it = 0; it < 16; ++it) { const int bj = it >> 3, ai = (it >> 2) & 1, m = it & 3;
;             if (it + 1 < 16) { const int bj2 = (it + 1) >> 3, ai2 = ((it + 1) >> 2) & 1, m2 = (it + 1) & 3; const bf16_t* p = ga + (size_t)(row0 + ai2 * HALF + m2 * 16) * GT_LD + bj2 * HALF;
;                 na[(it + 1) & 1] = *(const u32x4*)p; nb[(it + 1) & 1] = *(const u32x4*)(p + 1024); }
;             const u32x4 a = na[it & 1], b = nb[it & 1];
;             f32x4 v0 = acc[ai][bj][m][0], v1 = acc[ai][bj][m][1];
;             v0[0] *= bflo(a.x) * __builtin_amdgcn_rcpf(bflo(b.x)); v0[1] *= bfhi(a.x) * __builtin_amdgcn_rcpf(bfhi(b.x)); v0[2] *= bflo(a.y) * __builtin_amdgcn_rcpf(bflo(b.y)); v0[3] *= bfhi(a.y) * __builtin_amdgcn_rcpf(bfhi(b.y));
;             v1[0] *= bflo(a.z) * __builtin_amdgcn_rcpf(bflo(b.z)); v1[1] *= bfhi(a.z) * __builtin_amdgcn_rcpf(bfhi(b.z)); v1[2] *= bflo(a.w) * __builtin_amdgcn_rcpf(bflo(b.w)); v1[3] *= bfhi(a.w) * __builtin_amdgcn_rcpf(bfhi(b.w));
;             acc[ai][bj][m][0] = v0; acc[ai][bj][m][1] = v1;
;             asm volatile("" ::: "memory"); }
	v_lshlrev_b32_e32 v146, 16, v138
	v_and_b32_e32 v138, 0xffff0000, v138
	v_and_b32_e32 v149, 0xffff0000, v130
	v_lshlrev_b32_e32 v130, 16, v139
	v_rcp_f32_e32 v147, v138
	v_rcp_f32_e32 v138, v130
	v_and_b32_e32 v130, 0xffff0000, v139
	v_rcp_f32_e32 v139, v130
	v_lshlrev_b32_e32 v130, 16, v131
	v_and_b32_e32 v131, 0xffff0000, v131
	v_rcp_f32_e32 v146, v146
	v_pk_mul_f32 v[130:131], v[138:139], v[130:131]
	v_lshlrev_b32_e32 v138, 16, v132
	v_pk_mul_f32 v[40:41], v[40:41], v[130:131]
	v_lshlrev_b32_e32 v130, 16, v140
	v_and_b32_e32 v131, 0xffff0000, v140
	v_rcp_f32_e32 v130, v130
	v_rcp_f32_e32 v131, v131
	v_and_b32_e32 v139, 0xffff0000, v132
	v_pk_mul_f32 v[146:147], v[146:147], v[148:149]
	v_lshlrev_b32_e32 v132, 16, v133
	v_pk_mul_f32 v[130:131], v[130:131], v[138:139]
	v_pk_mul_f32 v[38:39], v[38:39], v[146:147]
	v_pk_mul_f32 v[34:35], v[34:35], v[130:131]
	v_lshlrev_b32_e32 v130, 16, v141
	v_and_b32_e32 v131, 0xffff0000, v141
	global_load_dwordx4 v[138:141], v[170:171], off offset:256
	global_load_dwordx4 v[146:149], v[170:171], off offset:2304
	v_rcp_f32_e32 v130, v130
	v_rcp_f32_e32 v131, v131
	v_and_b32_e32 v133, 0xffff0000, v133
	v_pk_mul_f32 v[130:131], v[130:131], v[132:133]
	s_nop 0
	v_pk_mul_f32 v[36:37], v[36:37], v[130:131]
	s_waitcnt vmcnt(3)
	v_lshlrev_b32_e32 v132, 16, v134
	s_waitcnt vmcnt(2)
	v_lshlrev_b32_e32 v130, 16, v142
	v_and_b32_e32 v131, 0xffff0000, v142
	v_rcp_f32_e32 v130, v130
	v_rcp_f32_e32 v131, v131
	v_and_b32_e32 v133, 0xffff0000, v134
	v_pk_mul_f32 v[130:131], v[130:131], v[132:133]
	s_nop 0
	v_pk_mul_f32 v[30:31], v[30:31], v[130:131]
	v_lshlrev_b32_e32 v130, 16, v143
	v_and_b32_e32 v131, 0xffff0000, v143
	v_rcp_f32_e32 v130, v130
	v_rcp_f32_e32 v131, v131
	v_lshlrev_b32_e32 v132, 16, v135
	v_and_b32_e32 v133, 0xffff0000, v135
	v_pk_mul_f32 v[130:131], v[130:131], v[132:133]
	s_nop 0
	v_pk_mul_f32 v[32:33], v[32:33], v[130:131]
	v_lshlrev_b32_e32 v130, 16, v144
	v_and_b32_e32 v131, 0xffff0000, v144
	v_rcp_f32_e32 v130, v130
	v_rcp_f32_e32 v131, v131
	v_lshlrev_b32_e32 v132, 16, v136
	v_and_b32_e32 v133, 0xffff0000, v136
	v_pk_mul_f32 v[130:131], v[130:131], v[132:133]
	s_nop 0
	v_pk_mul_f32 v[26:27], v[26:27], v[130:131]
	v_lshlrev_b32_e32 v130, 16, v145
	v_and_b32_e32 v131, 0xffff0000, v145
	v_rcp_f32_e32 v130, v130
	v_rcp_f32_e32 v131, v131
	v_lshlrev_b32_e32 v132, 16, v137
	v_and_b32_e32 v133, 0xffff0000, v137
	v_pk_mul_f32 v[130:131], v[130:131], v[132:133]
	s_nop 0
	v_pk_mul_f32 v[28:29], v[28:29], v[130:131]
	global_load_dwordx4 v[130:133], v[174:175], off offset:256
	global_load_dwordx4 v[134:137], v[174:175], off offset:2304
	s_waitcnt lgkmcnt(0)
	s_waitcnt vmcnt(3)
	v_lshlrev_b32_e32 v144, 16, v138
	s_waitcnt vmcnt(2)
	v_lshlrev_b32_e32 v142, 16, v146
	v_and_b32_e32 v143, 0xffff0000, v146
	v_rcp_f32_e32 v142, v142
	v_rcp_f32_e32 v143, v143
	v_and_b32_e32 v145, 0xffff0000, v138
	v_lshlrev_b32_e32 v138, 16, v147
	v_pk_mul_f32 v[142:143], v[142:143], v[144:145]
	s_nop 0
	v_pk_mul_f32 v[22:23], v[22:23], v[142:143]
	v_rcp_f32_e32 v142, v138
	v_and_b32_e32 v138, 0xffff0000, v147
	v_rcp_f32_e32 v143, v138
	v_lshlrev_b32_e32 v138, 16, v139
	v_and_b32_e32 v139, 0xffff0000, v139
	v_pk_mul_f32 v[138:139], v[142:143], v[138:139]
	s_nop 0
	v_pk_mul_f32 v[24:25], v[24:25], v[138:139]
	v_lshlrev_b32_e32 v138, 16, v148
	v_and_b32_e32 v139, 0xffff0000, v148
	v_rcp_f32_e32 v138, v138
	v_rcp_f32_e32 v139, v139
	v_lshlrev_b32_e32 v142, 16, v140
	v_and_b32_e32 v143, 0xffff0000, v140
	v_lshlrev_b32_e32 v140, 16, v141
	v_pk_mul_f32 v[138:139], v[138:139], v[142:143]
	v_and_b32_e32 v141, 0xffff0000, v141
	v_pk_mul_f32 v[18:19], v[18:19], v[138:139]
	v_lshlrev_b32_e32 v138, 16, v149
	v_and_b32_e32 v139, 0xffff0000, v149
	v_rcp_f32_e32 v138, v138
	v_rcp_f32_e32 v139, v139
	s_waitcnt vmcnt(1)
	v_lshlrev_b32_e32 v148, 16, v130
	v_pk_mul_f32 v[138:139], v[138:139], v[140:141]
	s_waitcnt vmcnt(0)
	v_lshlrev_b32_e32 v146, 16, v134
	v_pk_mul_f32 v[20:21], v[20:21], v[138:139]
	global_load_dwordx4 v[138:141], v[172:173], off offset:256
	global_load_dwordx4 v[142:145], v[172:173], off offset:2304
	v_and_b32_e32 v134, 0xffff0000, v134
	v_and_b32_e32 v149, 0xffff0000, v130
	v_lshlrev_b32_e32 v130, 16, v135
	v_rcp_f32_e32 v147, v134
	v_rcp_f32_e32 v134, v130
	v_and_b32_e32 v130, 0xffff0000, v135
	v_rcp_f32_e32 v135, v130
	v_lshlrev_b32_e32 v130, 16, v131
	v_and_b32_e32 v131, 0xffff0000, v131
	v_rcp_f32_e32 v146, v146
	v_pk_mul_f32 v[130:131], v[134:135], v[130:131]
	v_lshlrev_b32_e32 v134, 16, v132
	v_pk_mul_f32 v[16:17], v[16:17], v[130:131]
	v_lshlrev_b32_e32 v130, 16, v136
	v_and_b32_e32 v131, 0xffff0000, v136
	v_rcp_f32_e32 v130, v130
	v_rcp_f32_e32 v131, v131
	v_and_b32_e32 v135, 0xffff0000, v132
	v_lshlrev_b32_e32 v132, 16, v133
	v_and_b32_e32 v133, 0xffff0000, v133
	v_pk_mul_f32 v[130:131], v[130:131], v[134:135]
	v_pk_mul_f32 v[146:147], v[146:147], v[148:149]
	v_pk_mul_f32 v[10:11], v[10:11], v[130:131]
	v_lshlrev_b32_e32 v130, 16, v137
	v_and_b32_e32 v131, 0xffff0000, v137
	v_rcp_f32_e32 v130, v130
	v_rcp_f32_e32 v131, v131
	v_pk_mul_f32 v[14:15], v[14:15], v[146:147]
	v_pk_mul_f32 v[130:131], v[130:131], v[132:133]
	s_nop 0
	v_pk_mul_f32 v[12:13], v[12:13], v[130:131]
	s_waitcnt lgkmcnt(0)
	s_waitcnt vmcnt(1)
	v_lshlrev_b32_e32 v132, 16, v138
	s_waitcnt vmcnt(0)
	v_lshlrev_b32_e32 v130, 16, v142
	v_and_b32_e32 v131, 0xffff0000, v142
	v_rcp_f32_e32 v130, v130
	v_rcp_f32_e32 v131, v131
	v_and_b32_e32 v133, 0xffff0000, v138
	v_pk_mul_f32 v[130:131], v[130:131], v[132:133]
	s_nop 0
	v_pk_mul_f32 v[6:7], v[6:7], v[130:131]
	v_lshlrev_b32_e32 v130, 16, v143
	v_and_b32_e32 v131, 0xffff0000, v143
	v_rcp_f32_e32 v130, v130
	v_rcp_f32_e32 v131, v131
	v_lshlrev_b32_e32 v132, 16, v139
	v_and_b32_e32 v133, 0xffff0000, v139
	v_pk_mul_f32 v[130:131], v[130:131], v[132:133]
	s_nop 0
	v_pk_mul_f32 v[8:9], v[8:9], v[130:131]
	v_lshlrev_b32_e32 v130, 16, v144
	v_and_b32_e32 v131, 0xffff0000, v144
	v_rcp_f32_e32 v130, v130
	v_rcp_f32_e32 v131, v131
	v_lshlrev_b32_e32 v132, 16, v140
	v_and_b32_e32 v133, 0xffff0000, v140
	v_pk_mul_f32 v[130:131], v[130:131], v[132:133]
	s_nop 0
	v_pk_mul_f32 v[2:3], v[2:3], v[130:131]
	v_lshlrev_b32_e32 v130, 16, v145
	v_and_b32_e32 v131, 0xffff0000, v145
	v_rcp_f32_e32 v130, v130
	v_rcp_f32_e32 v131, v131
	v_lshlrev_b32_e32 v132, 16, v141
	v_and_b32_e32 v133, 0xffff0000, v141
	v_pk_mul_f32 v[130:131], v[130:131], v[132:133]
	s_nop 0
	v_pk_mul_f32 v[4:5], v[4:5], v[130:131]

; __device__ __forceinline__ unsigned pk2(float lo, float hi) { f32x2 v = {lo, hi}; bf16x2_t b = __builtin_convertvector(v, bf16x2_t); return __builtin_bit_cast(unsigned, b); }
; __device__ __forceinline__ float bflo(unsigned u) { return __uint_as_float(u << 16); }
; __device__ __forceinline__ float bfhi(unsigned u) { return __uint_as_float(u & 0xffff0000u); }
;     __device__ __forceinline__ void operator()(const Acc& acc, const Unit& u, int wr, int wc, int fr, int fq) const {
;         if (u.kind != 3) { gate_tile(acc, u, wr, wc, fr, fq); return; }
;         const int row0 = u.pm * BM + wr * 64 + fr, col0 = u.pn * BM + wc * 32 + 8 * fq;
;         const bf16_t* ga = GT + 2 * 1024 + col0;
;         u32x4 na[2];
;         na[0] = *(const u32x4*)(ga + (size_t)row0 * GT_LD);
; #pragma unroll
;         for (int it = 0; it < 16; ++it) { const int bj = it >> 3, ai = (it >> 2) & 1, m = it & 3; const size_t row = (size_t)(row0 + ai * HALF + m * 16);
;             if (it + 1 < 16) { const int bj2 = (it + 1) >> 3, ai2 = ((it + 1) >> 2) & 1, m2 = (it + 1) & 3; na[(it + 1) & 1] = *(const u32x4*)(ga + (size_t)(row0 + ai2 * HALF + m2 * 16) * GT_LD + bj2 * HALF); }
;             const u32x4 a = na[it & 1];
;             const f32x4 v0 = acc[ai][bj][m][0], v1 = acc[ai][bj][m][1];
;             u32x4 w; w.x = pk2(v0[0] * bflo(a.x), v0[1] * bfhi(a.x)); w.y = pk2(v0[2] * bflo(a.y), v0[3] * bfhi(a.y)); w.z = pk2(v1[0] * bflo(a.z), v1[1] * bfhi(a.z)); w.w = pk2(v1[2] * bflo(a.w), v1[3] * bfhi(a.w));
;             *(u32x4*)(MG + row * 1024 + col0 + bj * HALF) = w; asm volatile("" ::: "memory"); }
.LBB0_298:
	s_lshl_b32 s0, s14, 8
	s_or_b32 s0, s0, s96
	v_lshl_add_u32 v130, v161, 3, s0
	v_ashrrev_i32_e32 v131, 31, v130
	v_lshlrev_b64 v[132:133], 1, v[130:131]
	v_lshl_add_u64 v[136:137], s[82:83], 0, v[132:133]
	v_add_u32_e32 v144, 16, v146
	v_mad_i64_i32 v[130:131], s[0:1], v144, s33, v[136:137]
	v_mad_i64_i32 v[134:135], s[0:1], v146, s33, v[136:137]
	global_load_dwordx4 v[140:143], v[130:131], off
	global_load_dwordx4 v[160:163], v[134:135], off
	v_ashrrev_i32_e32 v147, 31, v146
	v_ashrrev_i32_e32 v145, 31, v144
	s_waitcnt lgkmcnt(0)
	s_waitcnt vmcnt(1)
	v_lshlrev_b32_e32 v148, 16, v140
	s_waitcnt vmcnt(0)
	v_lshlrev_b32_e32 v138, 16, v160
	v_and_b32_e32 v139, 0xffff0000, v160
	v_pk_mul_f32 v[126:127], v[126:127], v[138:139]
	v_add_u32_e32 v138, 32, v146
	v_cvt_pk_bf16_f32 v160, v126, v127
	v_lshlrev_b32_e32 v126, 16, v161
	v_and_b32_e32 v127, 0xffff0000, v161
	v_pk_mul_f32 v[126:127], v[128:129], v[126:127]
	v_mad_i64_i32 v[128:129], s[0:1], v138, s33, v[136:137]
	v_cvt_pk_bf16_f32 v161, v126, v127
	v_lshlrev_b32_e32 v126, 16, v162
	v_and_b32_e32 v127, 0xffff0000, v162
	v_pk_mul_f32 v[122:123], v[122:123], v[126:127]
	v_and_b32_e32 v149, 0xffff0000, v140
	v_cvt_pk_bf16_f32 v162, v122, v123
	v_lshlrev_b32_e32 v122, 16, v163
	v_and_b32_e32 v123, 0xffff0000, v163
	v_pk_mul_f32 v[122:123], v[124:125], v[122:123]
	v_lshlrev_b32_e32 v140, 16, v141
	v_cvt_pk_bf16_f32 v163, v122, v123
	v_lshlrev_b64 v[122:123], 11, v[146:147]
	v_lshl_add_u64 v[122:123], s[60:61], 0, v[122:123]
	v_lshl_add_u64 v[126:127], v[122:123], 0, v[132:133]
	global_store_dwordx4 v[126:127], v[160:163], off
	global_load_dwordx4 v[122:125], v[128:129], off
	v_and_b32_e32 v141, 0xffff0000, v141
	v_pk_mul_f32 v[118:119], v[118:119], v[148:149]
	v_pk_mul_f32 v[120:121], v[120:121], v[140:141]
	v_cvt_pk_bf16_f32 v118, v118, v119
	v_cvt_pk_bf16_f32 v119, v120, v121
	v_lshlrev_b32_e32 v120, 16, v142
	v_and_b32_e32 v121, 0xffff0000, v142
	v_pk_mul_f32 v[114:115], v[114:115], v[120:121]
	v_ashrrev_i32_e32 v139, 31, v138
	v_cvt_pk_bf16_f32 v120, v114, v115
	v_lshlrev_b32_e32 v114, 16, v143
	v_and_b32_e32 v115, 0xffff0000, v143
	v_pk_mul_f32 v[114:115], v[116:117], v[114:115]
	s_nop 0
	v_cvt_pk_bf16_f32 v121, v114, v115
	v_lshlrev_b64 v[114:115], 11, v[144:145]
	v_lshl_add_u64 v[114:115], s[60:61], 0, v[114:115]
	v_lshl_add_u64 v[114:115], v[114:115], 0, v[132:133]
	global_store_dwordx4 v[114:115], v[118:121], off
	s_nop 1
	v_add_u32_e32 v120, 48, v146
	v_mad_i64_i32 v[116:117], s[0:1], v120, s33, v[136:137]
	global_load_dwordx4 v[140:143], v[116:117], off
	v_ashrrev_i32_e32 v121, 31, v120
	s_waitcnt lgkmcnt(0)
	s_waitcnt vmcnt(2)
	v_lshlrev_b32_e32 v118, 16, v122
	v_and_b32_e32 v119, 0xffff0000, v122
	v_pk_mul_f32 v[110:111], v[110:111], v[118:119]
	v_add_u32_e32 v118, 0x80, v146
	v_cvt_pk_bf16_f32 v122, v110, v111
	v_lshlrev_b32_e32 v110, 16, v123
	v_and_b32_e32 v111, 0xffff0000, v123
	v_pk_mul_f32 v[110:111], v[112:113], v[110:111]
	v_mad_i64_i32 v[112:113], s[0:1], v118, s33, v[136:137]
	v_cvt_pk_bf16_f32 v123, v110, v111
	v_lshlrev_b32_e32 v110, 16, v124
	v_and_b32_e32 v111, 0xffff0000, v124
	v_pk_mul_f32 v[106:107], v[106:107], v[110:111]
	v_ashrrev_i32_e32 v119, 31, v118
	v_cvt_pk_bf16_f32 v124, v106, v107
	v_lshlrev_b32_e32 v106, 16, v125
	v_and_b32_e32 v107, 0xffff0000, v125
	v_pk_mul_f32 v[106:107], v[108:109], v[106:107]
	s_nop 0
	v_cvt_pk_bf16_f32 v125, v106, v107
	v_lshlrev_b64 v[106:107], 11, v[138:139]
	v_lshl_add_u64 v[106:107], s[60:61], 0, v[106:107]
	v_lshl_add_u64 v[110:111], v[106:107], 0, v[132:133]
	global_store_dwordx4 v[110:111], v[122:125], off
	global_load_dwordx4 v[106:109], v[112:113], off
	s_nop 0
	s_waitcnt vmcnt(2)
	v_lshlrev_b32_e32 v122, 16, v140
	v_and_b32_e32 v123, 0xffff0000, v140
	v_pk_mul_f32 v[102:103], v[102:103], v[122:123]
	v_lshlrev_b32_e32 v122, 16, v141
	v_and_b32_e32 v123, 0xffff0000, v141
	v_pk_mul_f32 v[104:105], v[104:105], v[122:123]
	v_cvt_pk_bf16_f32 v102, v102, v103
	v_cvt_pk_bf16_f32 v103, v104, v105
	v_lshlrev_b32_e32 v104, 16, v142
	v_and_b32_e32 v105, 0xffff0000, v142
	v_pk_mul_f32 v[98:99], v[98:99], v[104:105]
	s_nop 0
	v_cvt_pk_bf16_f32 v104, v98, v99
	v_lshlrev_b32_e32 v98, 16, v143
	v_and_b32_e32 v99, 0xffff0000, v143
	v_pk_mul_f32 v[98:99], v[100:101], v[98:99]
	s_nop 0
	v_cvt_pk_bf16_f32 v105, v98, v99
	v_lshlrev_b64 v[98:99], 11, v[120:121]
	v_lshl_add_u64 v[98:99], s[60:61], 0, v[98:99]
	v_lshl_add_u64 v[98:99], v[98:99], 0, v[132:133]
	global_store_dwordx4 v[98:99], v[102:105], off
	s_nop 1
	v_add_u32_e32 v104, 0x90, v146
	v_mad_i64_i32 v[100:101], s[0:1], v104, s33, v[136:137]
	global_load_dwordx4 v[120:123], v[100:101], off
	v_ashrrev_i32_e32 v105, 31, v104
	s_waitcnt lgkmcnt(0)
	s_waitcnt vmcnt(2)
	v_lshlrev_b32_e32 v102, 16, v106
	v_and_b32_e32 v103, 0xffff0000, v106
	v_pk_mul_f32 v[94:95], v[94:95], v[102:103]
	v_add_u32_e32 v102, 0xa0, v146
	v_cvt_pk_bf16_f32 v106, v94, v95
	v_lshlrev_b32_e32 v94, 16, v107
	v_and_b32_e32 v95, 0xffff0000, v107
	v_pk_mul_f32 v[94:95], v[96:97], v[94:95]
	v_mad_i64_i32 v[96:97], s[0:1], v102, s33, v[136:137]
	v_cvt_pk_bf16_f32 v107, v94, v95
	v_lshlrev_b32_e32 v94, 16, v108
	v_and_b32_e32 v95, 0xffff0000, v108
	v_pk_mul_f32 v[90:91], v[90:91], v[94:95]
	v_ashrrev_i32_e32 v103, 31, v102
	v_cvt_pk_bf16_f32 v108, v90, v91
	v_lshlrev_b32_e32 v90, 16, v109
	v_and_b32_e32 v91, 0xffff0000, v109
	v_pk_mul_f32 v[90:91], v[92:93], v[90:91]
	s_nop 0
	v_cvt_pk_bf16_f32 v109, v90, v91
	v_lshlrev_b64 v[90:91], 11, v[118:119]
	v_lshl_add_u64 v[90:91], s[60:61], 0, v[90:91]
	v_lshl_add_u64 v[94:95], v[90:91], 0, v[132:133]
	global_store_dwordx4 v[94:95], v[106:109], off
	global_load_dwordx4 v[90:93], v[96:97], off
	s_nop 0
	s_waitcnt vmcnt(2)
; __device__ __forceinline__ unsigned pk2(float lo, float hi) { f32x2 v = {lo, hi}; bf16x2_t b = __builtin_convertvector(v, bf16x2_t); return __builtin_bit_cast(unsigned, b); }
; __device__ __forceinline__ float bflo(unsigned u) { return __uint_as_float(u << 16); }
; __device__ __forceinline__ float bfhi(unsigned u) { return __uint_as_float(u & 0xffff0000u); }
;     __device__ __forceinline__ void operator()(const Acc& acc, const Unit& u, int wr, int wc, int fr, int fq) const {
;     ...
;         for (int it = 0; it < 16; ++it) { const int bj = it >> 3, ai = (it >> 2) & 1, m = it & 3; const size_t row = (size_t)(row0 + ai * HALF + m * 16);
;             if (it + 1 < 16) { const int bj2 = (it + 1) >> 3, ai2 = ((it + 1) >> 2) & 1, m2 = (it + 1) & 3; na[(it + 1) & 1] = *(const u32x4*)(ga + (size_t)(row0 + ai2 * HALF + m2 * 16) * GT_LD + bj2 * HALF); }
;             const u32x4 a = na[it & 1];
;             const f32x4 v0 = acc[ai][bj][m][0], v1 = acc[ai][bj][m][1];
;             u32x4 w; w.x = pk2(v0[0] * bflo(a.x), v0[1] * bfhi(a.x)); w.y = pk2(v0[2] * bflo(a.y), v0[3] * bfhi(a.y)); w.z = pk2(v1[0] * bflo(a.z), v1[1] * bfhi(a.z)); w.w = pk2(v1[2] * bflo(a.w), v1[3] * bfhi(a.w));
;             *(u32x4*)(MG + row * 1024 + col0 + bj * HALF) = w; asm volatile("" ::: "memory"); }
	v_lshlrev_b32_e32 v106, 16, v120
	v_and_b32_e32 v107, 0xffff0000, v120
	v_pk_mul_f32 v[86:87], v[86:87], v[106:107]
	v_lshlrev_b32_e32 v106, 16, v121
	v_and_b32_e32 v107, 0xffff0000, v121
	v_pk_mul_f32 v[88:89], v[88:89], v[106:107]
	v_cvt_pk_bf16_f32 v86, v86, v87
	v_cvt_pk_bf16_f32 v87, v88, v89
	v_lshlrev_b32_e32 v88, 16, v122
	v_and_b32_e32 v89, 0xffff0000, v122
	v_pk_mul_f32 v[82:83], v[82:83], v[88:89]
	s_nop 0
	v_cvt_pk_bf16_f32 v88, v82, v83
	v_lshlrev_b32_e32 v82, 16, v123
	v_and_b32_e32 v83, 0xffff0000, v123
	v_pk_mul_f32 v[82:83], v[84:85], v[82:83]
	s_nop 0
	v_cvt_pk_bf16_f32 v89, v82, v83
	v_lshlrev_b64 v[82:83], 11, v[104:105]
	v_lshl_add_u64 v[82:83], s[60:61], 0, v[82:83]
	v_lshl_add_u64 v[82:83], v[82:83], 0, v[132:133]
	global_store_dwordx4 v[82:83], v[86:89], off
	s_nop 1
	v_add_u32_e32 v86, 0xb0, v146
	v_mad_i64_i32 v[84:85], s[0:1], v86, s33, v[136:137]
	global_load_dwordx4 v[104:107], v[84:85], off
	v_ashrrev_i32_e32 v87, 31, v86
	s_waitcnt lgkmcnt(0)
	s_waitcnt vmcnt(2)
	v_lshlrev_b32_e32 v88, 16, v90
	v_and_b32_e32 v89, 0xffff0000, v90
	v_pk_mul_f32 v[78:79], v[78:79], v[88:89]
	s_nop 0
	v_cvt_pk_bf16_f32 v88, v78, v79
	v_lshlrev_b32_e32 v78, 16, v91
	v_and_b32_e32 v79, 0xffff0000, v91
	v_pk_mul_f32 v[78:79], v[80:81], v[78:79]
	s_waitcnt vmcnt(0)
	v_lshlrev_b32_e32 v80, 16, v104
	v_cvt_pk_bf16_f32 v89, v78, v79
	v_lshlrev_b32_e32 v78, 16, v92
	v_and_b32_e32 v79, 0xffff0000, v92
	v_pk_mul_f32 v[74:75], v[74:75], v[78:79]
	v_and_b32_e32 v81, 0xffff0000, v104
	v_cvt_pk_bf16_f32 v90, v74, v75
	v_lshlrev_b32_e32 v74, 16, v93
	v_and_b32_e32 v75, 0xffff0000, v93
	v_pk_mul_f32 v[74:75], v[76:77], v[74:75]
	v_pk_mul_f32 v[70:71], v[70:71], v[80:81]
	v_cvt_pk_bf16_f32 v91, v74, v75
	v_lshlrev_b64 v[74:75], 11, v[102:103]
	v_lshl_add_u64 v[74:75], s[60:61], 0, v[74:75]
	v_lshl_add_u64 v[78:79], v[74:75], 0, v[132:133]
	v_lshlrev_b32_e32 v80, 16, v105
	v_and_b32_e32 v81, 0xffff0000, v105
	global_store_dwordx4 v[78:79], v[88:91], off
	v_pk_mul_f32 v[72:73], v[72:73], v[80:81]
	v_cvt_pk_bf16_f32 v70, v70, v71
	v_cvt_pk_bf16_f32 v71, v72, v73
	v_lshlrev_b32_e32 v72, 16, v106
	v_and_b32_e32 v73, 0xffff0000, v106
	global_load_dwordx4 v[74:77], v[134:135], off offset:256
	v_pk_mul_f32 v[66:67], v[66:67], v[72:73]
	s_nop 0
	v_cvt_pk_bf16_f32 v72, v66, v67
	v_lshlrev_b32_e32 v66, 16, v107
	v_and_b32_e32 v67, 0xffff0000, v107
	v_pk_mul_f32 v[66:67], v[68:69], v[66:67]
	s_nop 0
	v_cvt_pk_bf16_f32 v73, v66, v67
	v_lshlrev_b64 v[66:67], 11, v[86:87]
	v_lshl_add_u64 v[66:67], s[60:61], 0, v[66:67]
	v_lshl_add_u64 v[66:67], v[66:67], 0, v[132:133]
	global_store_dwordx4 v[66:67], v[70:73], off
	global_load_dwordx4 v[68:71], v[130:131], off offset:256
	s_waitcnt lgkmcnt(0)
	s_waitcnt vmcnt(2)
	v_lshlrev_b32_e32 v72, 16, v74
	v_and_b32_e32 v73, 0xffff0000, v74
	v_pk_mul_f32 v[62:63], v[62:63], v[72:73]
	v_lshlrev_b32_e32 v72, 16, v75
	v_and_b32_e32 v73, 0xffff0000, v75
	v_pk_mul_f32 v[64:65], v[64:65], v[72:73]
	v_cvt_pk_bf16_f32 v62, v62, v63
	v_cvt_pk_bf16_f32 v63, v64, v65
	v_lshlrev_b32_e32 v64, 16, v76
	v_and_b32_e32 v65, 0xffff0000, v76
	v_pk_mul_f32 v[58:59], v[58:59], v[64:65]
	s_nop 0
	v_cvt_pk_bf16_f32 v64, v58, v59
	v_lshlrev_b32_e32 v58, 16, v77
	v_and_b32_e32 v59, 0xffff0000, v77
	v_pk_mul_f32 v[58:59], v[60:61], v[58:59]
	s_nop 0
	v_cvt_pk_bf16_f32 v65, v58, v59
	global_store_dwordx4 v[126:127], v[62:65], off offset:256
	global_load_dwordx4 v[58:61], v[128:129], off offset:256
	s_nop 0
	s_waitcnt vmcnt(2)
	v_lshlrev_b32_e32 v62, 16, v68
	v_and_b32_e32 v63, 0xffff0000, v68
	v_pk_mul_f32 v[54:55], v[54:55], v[62:63]
	v_lshlrev_b32_e32 v62, 16, v69
	v_and_b32_e32 v63, 0xffff0000, v69
	v_pk_mul_f32 v[56:57], v[56:57], v[62:63]
	v_cvt_pk_bf16_f32 v54, v54, v55
	v_cvt_pk_bf16_f32 v55, v56, v57
	v_lshlrev_b32_e32 v56, 16, v70
	v_and_b32_e32 v57, 0xffff0000, v70
	v_pk_mul_f32 v[50:51], v[50:51], v[56:57]
	s_nop 0
	v_cvt_pk_bf16_f32 v56, v50, v51
	v_lshlrev_b32_e32 v50, 16, v71
	v_and_b32_e32 v51, 0xffff0000, v71
	v_pk_mul_f32 v[50:51], v[52:53], v[50:51]
	s_nop 0
	v_cvt_pk_bf16_f32 v57, v50, v51
	global_store_dwordx4 v[114:115], v[54:57], off offset:256
	global_load_dwordx4 v[50:53], v[116:117], off offset:256
	s_waitcnt lgkmcnt(0)
	s_waitcnt vmcnt(2)
; __device__ __forceinline__ unsigned pk2(float lo, float hi) { f32x2 v = {lo, hi}; bf16x2_t b = __builtin_convertvector(v, bf16x2_t); return __builtin_bit_cast(unsigned, b); }
; __device__ __forceinline__ float bflo(unsigned u) { return __uint_as_float(u << 16); }
; __device__ __forceinline__ float bfhi(unsigned u) { return __uint_as_float(u & 0xffff0000u); }
;     __device__ __forceinline__ void operator()(const Acc& acc, const Unit& u, int wr, int wc, int fr, int fq) const {
;     ...
;         for (int it = 0; it < 16; ++it) { const int bj = it >> 3, ai = (it >> 2) & 1, m = it & 3; const size_t row = (size_t)(row0 + ai * HALF + m * 16);
;             if (it + 1 < 16) { const int bj2 = (it + 1) >> 3, ai2 = ((it + 1) >> 2) & 1, m2 = (it + 1) & 3; na[(it + 1) & 1] = *(const u32x4*)(ga + (size_t)(row0 + ai2 * HALF + m2 * 16) * GT_LD + bj2 * HALF); }
;             const u32x4 a = na[it & 1];
;             const f32x4 v0 = acc[ai][bj][m][0], v1 = acc[ai][bj][m][1];
;             u32x4 w; w.x = pk2(v0[0] * bflo(a.x), v0[1] * bfhi(a.x)); w.y = pk2(v0[2] * bflo(a.y), v0[3] * bfhi(a.y)); w.z = pk2(v1[0] * bflo(a.z), v1[1] * bfhi(a.z)); w.w = pk2(v1[2] * bflo(a.w), v1[3] * bfhi(a.w));
;             *(u32x4*)(MG + row * 1024 + col0 + bj * HALF) = w; asm volatile("" ::: "memory"); }
;     }
; template <class Epi, class Sched>
; __device__ __forceinline__ void gemm_phase(LAS unsigned char* lds, const Gemm g, const Sched& S, const Epi& E) {
;     ...
;         if (!has_next) break;
	v_lshlrev_b32_e32 v54, 16, v58
	v_and_b32_e32 v55, 0xffff0000, v58
	v_pk_mul_f32 v[46:47], v[46:47], v[54:55]
	v_lshlrev_b32_e32 v54, 16, v59
	v_and_b32_e32 v55, 0xffff0000, v59
	v_pk_mul_f32 v[48:49], v[48:49], v[54:55]
	v_cvt_pk_bf16_f32 v46, v46, v47
	v_cvt_pk_bf16_f32 v47, v48, v49
	v_lshlrev_b32_e32 v48, 16, v60
	v_and_b32_e32 v49, 0xffff0000, v60
	v_pk_mul_f32 v[42:43], v[42:43], v[48:49]
	s_nop 0
	v_cvt_pk_bf16_f32 v48, v42, v43
	v_lshlrev_b32_e32 v42, 16, v61
	v_and_b32_e32 v43, 0xffff0000, v61
	v_pk_mul_f32 v[42:43], v[44:45], v[42:43]
	s_nop 0
	v_cvt_pk_bf16_f32 v49, v42, v43
	global_store_dwordx4 v[110:111], v[46:49], off offset:256
	global_load_dwordx4 v[42:45], v[112:113], off offset:256
	s_nop 0
	s_waitcnt vmcnt(2)
	v_lshlrev_b32_e32 v46, 16, v50
	v_and_b32_e32 v47, 0xffff0000, v50
	v_pk_mul_f32 v[38:39], v[38:39], v[46:47]
	v_lshlrev_b32_e32 v46, 16, v51
	v_and_b32_e32 v47, 0xffff0000, v51
	v_pk_mul_f32 v[40:41], v[40:41], v[46:47]
	v_cvt_pk_bf16_f32 v38, v38, v39
	v_cvt_pk_bf16_f32 v39, v40, v41
	v_lshlrev_b32_e32 v40, 16, v52
	v_and_b32_e32 v41, 0xffff0000, v52
	v_pk_mul_f32 v[34:35], v[34:35], v[40:41]
	s_nop 0
	v_cvt_pk_bf16_f32 v40, v34, v35
	v_lshlrev_b32_e32 v34, 16, v53
	v_and_b32_e32 v35, 0xffff0000, v53
	v_pk_mul_f32 v[34:35], v[36:37], v[34:35]
	s_nop 0
	v_cvt_pk_bf16_f32 v41, v34, v35
	global_store_dwordx4 v[98:99], v[38:41], off offset:256
	global_load_dwordx4 v[34:37], v[100:101], off offset:256
	s_waitcnt lgkmcnt(0)
	s_waitcnt vmcnt(2)
	v_lshlrev_b32_e32 v38, 16, v42
	v_and_b32_e32 v39, 0xffff0000, v42
	v_pk_mul_f32 v[30:31], v[30:31], v[38:39]
	v_lshlrev_b32_e32 v38, 16, v43
	v_and_b32_e32 v39, 0xffff0000, v43
	v_pk_mul_f32 v[32:33], v[32:33], v[38:39]
	v_cvt_pk_bf16_f32 v30, v30, v31
	v_cvt_pk_bf16_f32 v31, v32, v33
	v_lshlrev_b32_e32 v32, 16, v44
	v_and_b32_e32 v33, 0xffff0000, v44
	v_pk_mul_f32 v[26:27], v[26:27], v[32:33]
	s_nop 0
	v_cvt_pk_bf16_f32 v32, v26, v27
	v_lshlrev_b32_e32 v26, 16, v45
	v_and_b32_e32 v27, 0xffff0000, v45
	v_pk_mul_f32 v[26:27], v[28:29], v[26:27]
	s_nop 0
	v_cvt_pk_bf16_f32 v33, v26, v27
	global_store_dwordx4 v[94:95], v[30:33], off offset:256
	global_load_dwordx4 v[26:29], v[96:97], off offset:256
	s_nop 0
	s_waitcnt vmcnt(2)
	v_lshlrev_b32_e32 v30, 16, v34
	v_and_b32_e32 v31, 0xffff0000, v34
	v_pk_mul_f32 v[22:23], v[22:23], v[30:31]
	v_lshlrev_b32_e32 v30, 16, v35
	v_and_b32_e32 v31, 0xffff0000, v35
	v_pk_mul_f32 v[24:25], v[24:25], v[30:31]
	v_cvt_pk_bf16_f32 v22, v22, v23
	v_cvt_pk_bf16_f32 v23, v24, v25
	v_lshlrev_b32_e32 v24, 16, v36
	v_and_b32_e32 v25, 0xffff0000, v36
	v_pk_mul_f32 v[18:19], v[18:19], v[24:25]
	s_nop 0
	v_cvt_pk_bf16_f32 v24, v18, v19
	v_lshlrev_b32_e32 v18, 16, v37
	v_and_b32_e32 v19, 0xffff0000, v37
	v_pk_mul_f32 v[18:19], v[20:21], v[18:19]
	s_nop 0
	v_cvt_pk_bf16_f32 v25, v18, v19
	global_store_dwordx4 v[82:83], v[22:25], off offset:256
	global_load_dwordx4 v[18:21], v[84:85], off offset:256
	s_waitcnt lgkmcnt(0)
	s_waitcnt vmcnt(2)
	v_lshlrev_b32_e32 v22, 16, v26
	v_and_b32_e32 v23, 0xffff0000, v26
	v_pk_mul_f32 v[14:15], v[14:15], v[22:23]
	v_lshlrev_b32_e32 v22, 16, v27
	v_and_b32_e32 v23, 0xffff0000, v27
	v_pk_mul_f32 v[16:17], v[16:17], v[22:23]
	v_cvt_pk_bf16_f32 v14, v14, v15
	v_cvt_pk_bf16_f32 v15, v16, v17
	v_lshlrev_b32_e32 v16, 16, v28
	v_and_b32_e32 v17, 0xffff0000, v28
	v_pk_mul_f32 v[10:11], v[10:11], v[16:17]
	s_nop 0
	v_cvt_pk_bf16_f32 v16, v10, v11
	v_lshlrev_b32_e32 v10, 16, v29
	v_and_b32_e32 v11, 0xffff0000, v29
	v_pk_mul_f32 v[10:11], v[12:13], v[10:11]
	s_nop 0
	v_cvt_pk_bf16_f32 v17, v10, v11
	global_store_dwordx4 v[78:79], v[14:17], off offset:256
	s_waitcnt vmcnt(1)
	v_lshlrev_b32_e32 v10, 16, v18
	v_and_b32_e32 v11, 0xffff0000, v18
	v_pk_mul_f32 v[6:7], v[6:7], v[10:11]
	v_lshlrev_b32_e32 v10, 16, v19
	v_and_b32_e32 v11, 0xffff0000, v19
	v_pk_mul_f32 v[8:9], v[8:9], v[10:11]
	v_cvt_pk_bf16_f32 v6, v6, v7
	v_cvt_pk_bf16_f32 v7, v8, v9
	v_lshlrev_b32_e32 v8, 16, v20
	v_and_b32_e32 v9, 0xffff0000, v20
	v_pk_mul_f32 v[2:3], v[2:3], v[8:9]
	s_nop 0
	v_cvt_pk_bf16_f32 v8, v2, v3
	v_lshlrev_b32_e32 v2, 16, v21
	v_and_b32_e32 v3, 0xffff0000, v21
	v_pk_mul_f32 v[2:3], v[4:5], v[2:3]
	s_nop 0
	v_cvt_pk_bf16_f32 v9, v2, v3
	global_store_dwordx4 v[66:67], v[6:9], off offset:256
	s_and_b64 vcc, exec, s[38:39]
	s_mov_b64 s[0:1], -1
	s_cbranch_vccnz .LBB0_273
